# stack + attention LDS-DMA issues placed in the softmax groups of tile A
# baseline (speedup 1.0000x reference)
; #define AT_LOAD(X, t) do { const size_t adv_ = (size_t)(t) * 64; sk##X = *(const u32x4*)(gk + adv_ * 1024); sv##X = *(const u32x4*)(gv + adv_ * 1024); if (rth) sr##X = *(const u32x4*)(gr + adv_ * 32); } while (0)
; __device__ __forceinline__ void attn_unit(LAS char* lds, const bf16_t* Qp, const bf16_t* KVp, const bf16_t* KRp, int ntiles, bf16_t* Yp, bool dry) {
;     ...
;     for (int t = 0; t < ntiles; t += 2) {
;         const int sb0 = (t & 2);
;         const bool more = (t + 2 < ntiles);
;         f32x16 pa0 = {}, pa1 = {}, pb0 = {}, pb1 = {};
;         AT_QK(sb0, pa0, pa1);
;         AT_QK(sb0 + 1, pb0, pb1);
;         if (t == 0) AT_SMPV(sb0, true, pa0, pa1); else AT_SMPV(sb0, false, pa0, pa1);
;         __builtin_amdgcn_sched_barrier(0);
;         if (more) { AT_LOAD(A, t + 2); AT_LOAD(B, t + 3); }
.Latt_nd2:
	ds_read_b64_tr_b16 v[98:99], v184 offset:55296
	ds_read_b64_tr_b16 v[100:101], v184 offset:55808
	ds_read_b64_tr_b16 v[102:103], v184 offset:59392
	s_waitcnt lgkmcnt(11)
	ds_read_b64_tr_b16 v[104:105], v184 offset:59904
	v_exp_f32_e32 v106, v106
	v_exp_f32_e32 v107, v107
	v_exp_f32_e32 v108, v108
	v_mfma_f32_32x32x16_bf16 v[34:49], v[74:77], v[232:235], v[34:49]
	v_exp_f32_e32 v109, v109
	v_exp_f32_e32 v110, v110
	v_exp_f32_e32 v111, v111
	v_exp_f32_e32 v112, v112
	v_exp_f32_e32 v113, v113
	v_cvt_pk_bf16_f32 v78, v106, v107
	v_cvt_pk_bf16_f32 v79, v108, v109
	v_mfma_f32_32x32x16_bf16 v[50:65], v[74:77], v[236:239], v[50:65]
	v_cvt_pk_bf16_f32 v80, v110, v111
	v_cvt_pk_bf16_f32 v81, v112, v113
	v_add_f32_e32 v178, v106, v107
	v_add_f32_e32 v179, v108, v109
	v_add_f32_e32 v180, v110, v111
	v_add_f32_e32 v181, v112, v113
	v_add_f32_e32 v178, v178, v179
	v_add_f32_e32 v180, v180, v181
	v_add_f32_e32 v178, v178, v180
	v_add_f32_e32 v210, v210, v178
	s_cmp_gt_u32 s35, 33
	s_cbranch_scc1 .Latt_nd3
	v_lshl_add_u64 v[130:131], v[130:131], 0, v[142:143]
	v_lshl_add_u64 v[132:133], v[132:133], 0, v[144:145]
	v_lshl_add_u64 v[134:135], v[134:135], 0, v[146:147]
	v_lshl_add_u64 v[136:137], v[136:137], 0, v[148:149]
	v_lshl_add_u64 v[138:139], v[138:139], 0, s[26:27]
	v_lshl_add_u64 v[140:141], v[140:141], 0, s[26:27]
